# v68 + mixer queue order: context items dequeued right after the differential items (before NA and spatial-gating)
# speedup vs baseline: 1.0038x; 1.0038x over previous
.LBB0_94:
	s_barrier
	s_mov_b64 s[0:1], exec
	v_readfirstlane_b32 s98, v155
	s_lshr_b32 s98, s98, 6
	s_cmp_lg_u32 s98, 0
	s_cbranch_scc1 .LBB0_98
	s_waitcnt vmcnt(0)
	v_readlane_b32 s98, v255, 32
	s_cmp_ge_u32 s98, s93
	s_cbranch_scc1 .Ldq_done
	s_cmp_lt_u32 s98, 0x100
	s_cbranch_scc0 .Ldq_o0
	s_branch .Ldq_done
	s_nop 0
	s_nop 0
	s_nop 0
	s_nop 0
	s_nop 0
	s_nop 0
	s_nop 0
	s_nop 0
	s_nop 0
	s_nop 0
	s_nop 0
	s_nop 0
	s_nop 0
	s_nop 0
	s_nop 0
	s_nop 0
	s_nop 0
	s_nop 0
	s_nop 0
	s_nop 0
	s_nop 0
	s_nop 0
	s_nop 0
	s_nop 0
	s_nop 0
	s_nop 0
	s_nop 0
	s_nop 0
	s_nop 0
	s_nop 0
.Ldq_o0:
	s_sub_i32 s98, s98, 0x100
	s_cmp_lt_u32 s98, 0x200
	s_cbranch_scc0 .Ldq_o1
	s_add_i32 s98, s98, 0x100
	s_branch .Ldq_done
.Ldq_o1:
	s_sub_i32 s98, s98, 0x200
	s_sub_i32 s99, s93, s37
	s_cmp_lt_u32 s98, s99
	s_cbranch_scc0 .Ldq_o2
	s_add_i32 s98, s98, s37
	s_branch .Ldq_done
.Ldq_o2:
	s_sub_i32 s98, s98, s99
	s_cmp_lt_u32 s98, 0x200
	s_cbranch_scc0 .Ldq_o3
	s_add_i32 s98, s98, 0x300
	s_branch .Ldq_done
.Ldq_o3:
	s_sub_i32 s98, s98, 0x200
	s_sub_i32 s99, s37, 0x500
	s_add_i32 s98, s98, 0x500
